# qkconv conv loop: conv weights/bias/column pointers hoisted out of the trip loop (11 -> 3 loads per trip), hand-scheduled counted waits
# speedup vs baseline: 1.0066x; 1.0066x over previous
.LBB0_1608:
	s_or_b64 exec, exec, s[18:19]
	v_lshl_add_u32 v2, s2, 9, v128
	s_mov_b32 s0, 0x240000
	v_cmp_gt_i32_e32 vcc, s0, v2
	s_and_saveexec_b64 s[6:7], vcc
	v_readlane_b32 s36, v252, 16
	v_readlane_b32 s50, v252, 30
	v_readlane_b32 s51, v252, 31
	v_readlane_b32 s37, v252, 17
	v_readlane_b32 s38, v252, 18
	v_readlane_b32 s39, v252, 19
	v_readlane_b32 s40, v252, 20
	v_readlane_b32 s41, v252, 21
	v_readlane_b32 s42, v252, 22
	v_readlane_b32 s43, v252, 23
	v_readlane_b32 s44, v252, 24
	v_readlane_b32 s45, v252, 25
	v_readlane_b32 s46, v252, 26
	v_readlane_b32 s47, v252, 27
	v_readlane_b32 s48, v252, 28
	v_readlane_b32 s49, v252, 29
	s_cbranch_execz .LBB0_1611
	v_lshlrev_b32_e32 v0, 3, v128
	s_mov_b64 s[26:27], s[50:51]
	s_lshl_b32 s14, s22, 9
	v_lshl_add_u32 v3, s2, 12, v0
	s_lshl_b32 s15, s22, 12
	s_mov_b64 s[8:9], 0
	s_movk_i32 s16, 0x4000
	s_waitcnt vmcnt(2)
	v_mov_b32_e32 v4, 0xff
	v_mov_b32_e32 v5, 0x7ff
	v_mov_b32_e32 v6, 0x100
	v_mov_b32_e32 v7, 0x800
	v_mov_b32_e32 v1, 0
	s_mov_b64 s[10:11], 0x1000
	s_mov_b64 s[12:13], 0x2000
	s_movk_i32 s17, 0x2000
	s_movk_i32 s18, 0x1ff
	v_mov_b32_e32 v8, 0x3e000000
	s_mov_b32 s19, 0x23ffff
	v_and_b32_e32 v9, 0x3f8, v3
	v_lshlrev_b32_e32 v0, 2, v9
	v_add_u32_e32 v106, 0x1000, v0
	v_add_u32_e32 v107, 0x2000, v0
	global_load_dwordx4 v[74:77], v0, s[72:73]
	global_load_dwordx4 v[78:81], v0, s[72:73] offset:16
	global_load_dwordx4 v[82:85], v0, s[26:27]
	global_load_dwordx4 v[86:89], v0, s[26:27] offset:16
	global_load_dwordx4 v[90:93], v106, s[26:27]
	global_load_dwordx4 v[94:97], v106, s[26:27] offset:16
	global_load_dwordx4 v[98:101], v107, s[26:27]
	global_load_dwordx4 v[102:105], v107, s[26:27] offset:16
	v_lshlrev_b32_e32 v68, 1, v9
	v_mov_b32_e32 v69, v1
	v_cmp_lt_u32_e64 s[0:1], s18, v9
	v_lshl_add_u64 v[70:71], s[88:89], 0, v[68:69]
	v_lshl_add_u64 v[68:69], s[4:5], 0, v[68:69]
	v_cndmask_b32_e64 v67, 1.0, v8, s[0:1]
.Lqkc_loop:
	v_ashrrev_i32_e32 v26, 7, v2
	v_cmp_gt_i32_e32 vcc, s16, v26
	v_ashrrev_i32_e32 v27, 31, v26
	v_lshlrev_b64 v[30:31], 11, v[26:27]
	v_cndmask_b32_e32 v10, v4, v5, vcc
	v_cndmask_b32_e32 v33, v6, v7, vcc
	v_and_b32_e32 v32, v10, v26
	v_add_u32_e32 v48, -1, v33
	v_add_u32_e32 v0, -1, v32
	v_add_u32_e32 v36, 1, v32
	v_sub_u32_e32 v49, v26, v32
	v_cmp_lt_u32_e32 vcc, v32, v33
	v_min_u32_e32 v50, v32, v48
	v_min_u32_e32 v51, v36, v48
	v_cndmask_b32_e64 v56, 0, 1.0, vcc
	v_cmp_lt_u32_e32 vcc, v0, v33
	v_max_i32_e32 v0, 0, v0
	v_min_u32_e32 v0, v0, v48
	v_cndmask_b32_e64 v57, 0, 1.0, vcc
	v_cmp_lt_u32_e32 vcc, v36, v33
	v_add_u32_e32 v42, v49, v50
	v_add_u32_e32 v44, v51, v49
	v_cndmask_b32_e64 v58, 0, 1.0, vcc
	v_add_u32_e32 v48, v0, v49
	v_ashrrev_i32_e32 v43, 31, v42
	v_ashrrev_i32_e32 v45, 31, v44
	v_ashrrev_i32_e32 v49, 31, v48
	v_lshlrev_b64 v[42:43], 11, v[42:43]
	v_lshlrev_b64 v[44:45], 11, v[44:45]
	v_lshlrev_b64 v[48:49], 11, v[48:49]
	v_lshl_add_u64 v[108:109], v[68:69], 0, v[48:49]
	v_lshl_add_u64 v[110:111], v[68:69], 0, v[42:43]
	v_lshl_add_u64 v[112:113], v[68:69], 0, v[44:45]
	v_lshl_add_u64 v[54:55], v[70:71], 0, v[30:31]
	global_load_dwordx4 v[46:49], v[108:109], off
	global_load_dwordx4 v[50:53], v[110:111], off
	global_load_dwordx4 v[42:45], v[112:113], off
	v_add_u32_e32 v2, s14, v2
	v_add_u32_e32 v3, s15, v3
	v_cmp_lt_i32_e64 s[0:1], s19, v2
	s_nop 0
	s_or_b64 s[8:9], s[0:1], s[8:9]
	s_waitcnt vmcnt(2)
	v_mul_f32_e32 v18, v57, v82
	v_mul_f32_e32 v19, v57, v83
	v_mul_f32_e32 v20, v57, v84
	v_mul_f32_e32 v21, v57, v85
	v_mul_f32_e32 v22, v57, v86
	v_mul_f32_e32 v23, v57, v87
	v_mul_f32_e32 v24, v57, v88
	v_mul_f32_e32 v25, v57, v89
	v_lshlrev_b32_e32 v59, 16, v46
	v_and_b32_e32 v60, 0xffff0000, v46
	v_lshlrev_b32_e32 v61, 16, v47
	v_and_b32_e32 v62, 0xffff0000, v47
	v_lshlrev_b32_e32 v63, 16, v48
	v_and_b32_e32 v64, 0xffff0000, v48
	v_lshlrev_b32_e32 v65, 16, v49
	v_and_b32_e32 v66, 0xffff0000, v49
	v_fma_f32 v10, v18, v59, v74
	v_fma_f32 v11, v19, v60, v75
	v_fma_f32 v12, v20, v61, v76
	v_fma_f32 v13, v21, v62, v77
	v_fma_f32 v14, v22, v63, v78
	v_fma_f32 v15, v23, v64, v79
	v_fma_f32 v16, v24, v65, v80
	v_fma_f32 v17, v25, v66, v81
	s_waitcnt vmcnt(1)
	v_mul_f32_e32 v26, v56, v90
	v_mul_f32_e32 v27, v56, v91
	v_mul_f32_e32 v28, v56, v92
	v_mul_f32_e32 v29, v56, v93
	v_mul_f32_e32 v30, v56, v94
	v_mul_f32_e32 v31, v56, v95
	v_mul_f32_e32 v32, v56, v96
	v_mul_f32_e32 v33, v56, v97
	v_lshlrev_b32_e32 v59, 16, v50
	v_and_b32_e32 v60, 0xffff0000, v50
	v_lshlrev_b32_e32 v61, 16, v51
	v_and_b32_e32 v62, 0xffff0000, v51
	v_lshlrev_b32_e32 v63, 16, v52
	v_and_b32_e32 v64, 0xffff0000, v52
	v_lshlrev_b32_e32 v65, 16, v53
	v_and_b32_e32 v66, 0xffff0000, v53
	v_fmac_f32_e32 v10, v26, v59
	v_fmac_f32_e32 v11, v27, v60
	v_fmac_f32_e32 v12, v28, v61
	v_fmac_f32_e32 v13, v29, v62
	v_fmac_f32_e32 v14, v30, v63
	v_fmac_f32_e32 v15, v31, v64
	v_fmac_f32_e32 v16, v32, v65
	v_fmac_f32_e32 v17, v33, v66
	s_waitcnt vmcnt(0)
	v_mul_f32_e32 v34, v58, v98
	v_mul_f32_e32 v35, v58, v99
	v_mul_f32_e32 v36, v58, v100
	v_mul_f32_e32 v37, v58, v101
	v_mul_f32_e32 v38, v58, v102
	v_mul_f32_e32 v39, v58, v103
	v_mul_f32_e32 v40, v58, v104
	v_mul_f32_e32 v41, v58, v105
	v_lshlrev_b32_e32 v59, 16, v42
	v_and_b32_e32 v60, 0xffff0000, v42
	v_lshlrev_b32_e32 v61, 16, v43
	v_and_b32_e32 v62, 0xffff0000, v43
	v_lshlrev_b32_e32 v63, 16, v44
	v_and_b32_e32 v64, 0xffff0000, v44
	v_lshlrev_b32_e32 v65, 16, v45
	v_and_b32_e32 v66, 0xffff0000, v45
	v_fmac_f32_e32 v10, v34, v59
	v_fmac_f32_e32 v11, v35, v60
	v_fmac_f32_e32 v12, v36, v61
	v_fmac_f32_e32 v13, v37, v62
	v_fmac_f32_e32 v14, v38, v63
	v_fmac_f32_e32 v15, v39, v64
	v_fmac_f32_e32 v16, v40, v65
	v_fmac_f32_e32 v17, v41, v66
	v_mul_f32_e32 v18, 0xbfb8aa3b, v10
	v_mul_f32_e32 v19, 0xbfb8aa3b, v11
	v_mul_f32_e32 v20, 0xbfb8aa3b, v12
	v_mul_f32_e32 v21, 0xbfb8aa3b, v13
	v_mul_f32_e32 v22, 0xbfb8aa3b, v14
	v_mul_f32_e32 v23, 0xbfb8aa3b, v15
	v_mul_f32_e32 v24, 0xbfb8aa3b, v16
	v_mul_f32_e32 v25, 0xbfb8aa3b, v17
	v_exp_f32_e32 v18, v18
	v_exp_f32_e32 v19, v19
	v_exp_f32_e32 v20, v20
	v_exp_f32_e32 v21, v21
	v_exp_f32_e32 v22, v22
	v_exp_f32_e32 v23, v23
	v_exp_f32_e32 v24, v24
	v_exp_f32_e32 v25, v25
	v_add_f32_e32 v18, 1.0, v18
	v_add_f32_e32 v19, 1.0, v19
	v_add_f32_e32 v20, 1.0, v20
	v_add_f32_e32 v21, 1.0, v21
	v_add_f32_e32 v22, 1.0, v22
	v_add_f32_e32 v23, 1.0, v23
	v_add_f32_e32 v24, 1.0, v24
	v_add_f32_e32 v25, 1.0, v25
	v_rcp_f32_e32 v18, v18
	v_rcp_f32_e32 v19, v19
	v_rcp_f32_e32 v20, v20
	v_rcp_f32_e32 v21, v21
	v_rcp_f32_e32 v22, v22
	v_rcp_f32_e32 v23, v23
	v_rcp_f32_e32 v24, v24
	v_rcp_f32_e32 v25, v25
	v_mul_f32_e32 v18, v10, v18
	v_mul_f32_e32 v19, v11, v19
	v_mul_f32_e32 v20, v12, v20
	v_mul_f32_e32 v21, v13, v21
	v_mul_f32_e32 v22, v14, v22
	v_mul_f32_e32 v23, v15, v23
	v_mul_f32_e32 v24, v16, v24
	v_mul_f32_e32 v25, v17, v25
	v_mul_f32_e32 v18, v67, v18
	v_mul_f32_e32 v19, v67, v19
	v_mul_f32_e32 v20, v67, v20
	v_mul_f32_e32 v21, v67, v21
	v_mul_f32_e32 v22, v67, v22
	v_mul_f32_e32 v23, v67, v23
	v_mul_f32_e32 v24, v67, v24
	v_mul_f32_e32 v25, v67, v25
	v_cvt_pk_bf16_f32 v10, v18, v19
	v_cvt_pk_bf16_f32 v11, v20, v21
	v_cvt_pk_bf16_f32 v12, v22, v23
	v_cvt_pk_bf16_f32 v13, v24, v25
	global_store_dwordx4 v[54:55], v[10:13], off
	s_andn2_b64 exec, exec, s[8:9]
	s_cbranch_execnz .Lqkc_loop
